# out-projection residual epilogue: each batch of base loads issued before the previous batch of stores (counted vmcnt), on top of MLA row-sum move
# speedup vs baseline: 1.0016x; 1.0016x over previous
.LBB0_1170:
	s_ashr_i32 s1, s86, 31
	s_add_i32 s0, s86, 0xffffff80
	v_readlane_b32 s36, v243, 63
	v_readlane_b32 s22, v242, 19
	s_cmpk_lt_i32 s86, 0x80
	s_movk_i32 s13, 0x4800
	v_readlane_b32 s48, v242, 11
	v_readlane_b32 s49, v242, 12
	v_readlane_b32 s23, v242, 20
	s_cselect_b32 s13, s13, 0x9000
	s_cselect_b32 s15, s49, s23
	s_cselect_b32 s21, s48, s22
	s_cselect_b32 s0, s86, s0
	s_cselect_b32 s1, s1, 0
	s_cmp_gt_i32 s86, 63
	s_cselect_b32 s13, s13, 0
	s_lshl_b32 s13, s13, 2
	s_add_u32 s22, s87, s13
	v_lshl_or_b32 v90, s68, 8, v169
	s_addc_u32 s23, s90, 0
	s_lshl_b64 s[0:1], s[0:1], 21
	v_ashrrev_i32_e32 v91, 31, v90
	s_add_u32 s0, s21, s0
	v_lshlrev_b64 v[176:177], 2, v[90:91]
	s_addc_u32 s1, s15, s1
	v_lshl_add_u64 v[90:91], s[22:23], 0, v[176:177]
	v_lshl_add_u64 v[176:177], s[0:1], 0, v[176:177]
	v_lshl_add_u64 v[190:191], v[176:177], 0, v[146:147]
	v_lshl_add_u64 v[188:189], v[176:177], 0, v[148:149]
	v_lshl_add_u64 v[186:187], v[176:177], 0, v[150:151]
	v_lshl_add_u64 v[184:185], v[176:177], 0, v[152:153]
	v_lshl_add_u64 v[182:183], v[176:177], 0, v[154:155]
	v_lshl_add_u64 v[180:181], v[176:177], 0, v[156:157]
	v_lshl_add_u64 v[178:179], v[176:177], 0, v[158:159]
	v_lshl_add_u64 v[176:177], v[176:177], 0, v[160:161]
	global_load_dwordx4 v[196:199], v[90:91], off
	global_load_dwordx4 v[138:141], v[90:91], off offset:64
	global_load_dwordx4 v[134:137], v[90:91], off offset:512
	s_nop 0
	global_load_dwordx4 v[90:93], v[90:91], off offset:576
	s_mov_b64 s[0:1], -1
	global_load_dwordx4 v[200:203], v[190:191], off
	global_load_dwordx4 v[204:207], v[188:189], off
	global_load_dwordx4 v[208:211], v[186:187], off
	global_load_dwordx4 v[212:215], v[184:185], off
	global_load_dwordx4 v[216:219], v[182:183], off
	global_load_dwordx4 v[220:223], v[180:181], off
	global_load_dwordx4 v[224:227], v[178:179], off
	global_load_dwordx4 v[228:231], v[176:177], off
	s_andn2_b64 vcc, exec, s[2:3]
	v_readlane_b32 s37, v242, 0
	v_readlane_b32 s38, v242, 1
	v_readlane_b32 s39, v242, 2
	v_readlane_b32 s40, v242, 3
	v_readlane_b32 s41, v242, 4
	v_readlane_b32 s42, v242, 5
	v_readlane_b32 s43, v242, 6
	v_readlane_b32 s44, v242, 7
	v_readlane_b32 s45, v242, 8
	v_readlane_b32 s46, v242, 9
	v_readlane_b32 s47, v242, 10
	v_readlane_b32 s50, v242, 13
	v_readlane_b32 s51, v242, 14
	s_waitcnt vmcnt(0)
	v_pk_fma_f32 v[132:133], v[132:133], v[198:199], v[202:203]
	v_pk_fma_f32 v[130:131], v[130:131], v[196:197], v[200:201]
	v_pk_fma_f32 v[128:129], v[128:129], v[198:199], v[206:207]
	v_pk_fma_f32 v[126:127], v[126:127], v[196:197], v[204:205]
	v_pk_fma_f32 v[124:125], v[124:125], v[198:199], v[210:211]
	v_pk_fma_f32 v[122:123], v[122:123], v[196:197], v[208:209]
	v_pk_fma_f32 v[120:121], v[120:121], v[198:199], v[214:215]
	v_pk_fma_f32 v[118:119], v[118:119], v[196:197], v[212:213]
	v_pk_fma_f32 v[116:117], v[116:117], v[198:199], v[218:219]
	v_pk_fma_f32 v[114:115], v[114:115], v[196:197], v[216:217]
	v_pk_fma_f32 v[112:113], v[112:113], v[198:199], v[222:223]
	v_pk_fma_f32 v[110:111], v[110:111], v[196:197], v[220:221]
	v_pk_fma_f32 v[108:109], v[108:109], v[198:199], v[226:227]
	v_pk_fma_f32 v[106:107], v[106:107], v[196:197], v[224:225]
	v_pk_fma_f32 v[104:105], v[104:105], v[198:199], v[230:231]
	v_pk_fma_f32 v[102:103], v[102:103], v[196:197], v[228:229]
	global_load_dwordx4 v[200:203], v[190:191], off offset:64
	global_load_dwordx4 v[204:207], v[188:189], off offset:64
	global_load_dwordx4 v[208:211], v[186:187], off offset:64
	global_load_dwordx4 v[212:215], v[184:185], off offset:64
	global_load_dwordx4 v[216:219], v[182:183], off offset:64
	global_load_dwordx4 v[220:223], v[180:181], off offset:64
	global_load_dwordx4 v[224:227], v[178:179], off offset:64
	global_load_dwordx4 v[228:231], v[176:177], off offset:64
	global_store_dwordx4 v[190:191], v[130:133], off
	global_store_dwordx4 v[188:189], v[126:129], off
	global_store_dwordx4 v[186:187], v[122:125], off
	global_store_dwordx4 v[184:185], v[118:121], off
	global_store_dwordx4 v[182:183], v[114:117], off
	global_store_dwordx4 v[180:181], v[110:113], off
	global_store_dwordx4 v[178:179], v[106:109], off
	global_store_dwordx4 v[176:177], v[102:105], off
	s_waitcnt vmcnt(15)
	v_pk_fma_f32 v[100:101], v[100:101], v[140:141], v[202:203]
	v_pk_fma_f32 v[98:99], v[98:99], v[138:139], v[200:201]
	s_waitcnt vmcnt(14)
	v_pk_fma_f32 v[96:97], v[96:97], v[140:141], v[206:207]
	v_pk_fma_f32 v[94:95], v[94:95], v[138:139], v[204:205]
	s_waitcnt vmcnt(13)
	v_pk_fma_f32 v[88:89], v[88:89], v[140:141], v[210:211]
	v_pk_fma_f32 v[86:87], v[86:87], v[138:139], v[208:209]
	s_waitcnt vmcnt(12)
	v_pk_fma_f32 v[84:85], v[84:85], v[140:141], v[214:215]
	v_pk_fma_f32 v[82:83], v[82:83], v[138:139], v[212:213]
	s_waitcnt vmcnt(11)
	v_pk_fma_f32 v[80:81], v[80:81], v[140:141], v[218:219]
	v_pk_fma_f32 v[78:79], v[78:79], v[138:139], v[216:217]
	s_waitcnt vmcnt(10)
	v_pk_fma_f32 v[76:77], v[76:77], v[140:141], v[222:223]
	v_pk_fma_f32 v[74:75], v[74:75], v[138:139], v[220:221]
	s_waitcnt vmcnt(9)
	v_pk_fma_f32 v[72:73], v[72:73], v[140:141], v[226:227]
	v_pk_fma_f32 v[70:71], v[70:71], v[138:139], v[224:225]
	s_waitcnt vmcnt(8)
	v_pk_fma_f32 v[68:69], v[68:69], v[140:141], v[230:231]
	v_pk_fma_f32 v[66:67], v[66:67], v[138:139], v[228:229]
	global_load_dwordx4 v[200:203], v[190:191], off offset:512
	global_load_dwordx4 v[204:207], v[188:189], off offset:512
	global_load_dwordx4 v[208:211], v[186:187], off offset:512
	global_load_dwordx4 v[212:215], v[184:185], off offset:512
	global_load_dwordx4 v[216:219], v[182:183], off offset:512
	global_load_dwordx4 v[220:223], v[180:181], off offset:512
	global_load_dwordx4 v[224:227], v[178:179], off offset:512
	global_load_dwordx4 v[228:231], v[176:177], off offset:512
	global_store_dwordx4 v[190:191], v[98:101], off offset:64
	global_store_dwordx4 v[188:189], v[94:97], off offset:64
	global_store_dwordx4 v[186:187], v[86:89], off offset:64
	global_store_dwordx4 v[184:185], v[82:85], off offset:64
	global_store_dwordx4 v[182:183], v[78:81], off offset:64
	global_store_dwordx4 v[180:181], v[74:77], off offset:64
	global_store_dwordx4 v[178:179], v[70:73], off offset:64
	global_store_dwordx4 v[176:177], v[66:69], off offset:64
	s_waitcnt vmcnt(15)
	v_pk_fma_f32 v[64:65], v[64:65], v[136:137], v[202:203]
	v_pk_fma_f32 v[62:63], v[62:63], v[134:135], v[200:201]
	s_waitcnt vmcnt(14)
	v_pk_fma_f32 v[60:61], v[60:61], v[136:137], v[206:207]
	v_pk_fma_f32 v[58:59], v[58:59], v[134:135], v[204:205]
	s_waitcnt vmcnt(13)
	v_pk_fma_f32 v[56:57], v[56:57], v[136:137], v[210:211]
	v_pk_fma_f32 v[54:55], v[54:55], v[134:135], v[208:209]
	s_waitcnt vmcnt(12)
	v_pk_fma_f32 v[52:53], v[52:53], v[136:137], v[214:215]
	v_pk_fma_f32 v[50:51], v[50:51], v[134:135], v[212:213]
	s_waitcnt vmcnt(11)
	v_pk_fma_f32 v[48:49], v[48:49], v[136:137], v[218:219]
	v_pk_fma_f32 v[46:47], v[46:47], v[134:135], v[216:217]
	s_waitcnt vmcnt(10)
	v_pk_fma_f32 v[44:45], v[44:45], v[136:137], v[222:223]
	v_pk_fma_f32 v[42:43], v[42:43], v[134:135], v[220:221]
	s_waitcnt vmcnt(9)
	v_pk_fma_f32 v[40:41], v[40:41], v[136:137], v[226:227]
	v_pk_fma_f32 v[38:39], v[38:39], v[134:135], v[224:225]
	s_waitcnt vmcnt(8)
	v_pk_fma_f32 v[36:37], v[36:37], v[136:137], v[230:231]
	v_pk_fma_f32 v[34:35], v[34:35], v[134:135], v[228:229]
	global_load_dwordx4 v[200:203], v[190:191], off offset:576
	global_load_dwordx4 v[204:207], v[188:189], off offset:576
	global_load_dwordx4 v[208:211], v[186:187], off offset:576
	global_load_dwordx4 v[212:215], v[184:185], off offset:576
	global_load_dwordx4 v[216:219], v[182:183], off offset:576
	global_load_dwordx4 v[220:223], v[180:181], off offset:576
	global_load_dwordx4 v[224:227], v[178:179], off offset:576
	global_load_dwordx4 v[228:231], v[176:177], off offset:576
	global_store_dwordx4 v[190:191], v[62:65], off offset:512
	global_store_dwordx4 v[188:189], v[58:61], off offset:512
	global_store_dwordx4 v[186:187], v[54:57], off offset:512
	global_store_dwordx4 v[184:185], v[50:53], off offset:512
	global_store_dwordx4 v[182:183], v[46:49], off offset:512
	global_store_dwordx4 v[180:181], v[42:45], off offset:512
	global_store_dwordx4 v[178:179], v[38:41], off offset:512
	global_store_dwordx4 v[176:177], v[34:37], off offset:512
	s_waitcnt vmcnt(15)
	v_pk_fma_f32 v[32:33], v[32:33], v[92:93], v[202:203]
	v_pk_fma_f32 v[30:31], v[30:31], v[90:91], v[200:201]
	s_waitcnt vmcnt(14)
	v_pk_fma_f32 v[28:29], v[28:29], v[92:93], v[206:207]
	v_pk_fma_f32 v[26:27], v[26:27], v[90:91], v[204:205]
	s_waitcnt vmcnt(13)
	v_pk_fma_f32 v[24:25], v[24:25], v[92:93], v[210:211]
	v_pk_fma_f32 v[22:23], v[22:23], v[90:91], v[208:209]
	s_waitcnt vmcnt(12)
	v_pk_fma_f32 v[20:21], v[20:21], v[92:93], v[214:215]
	v_pk_fma_f32 v[18:19], v[18:19], v[90:91], v[212:213]
	s_waitcnt vmcnt(11)
	v_pk_fma_f32 v[16:17], v[16:17], v[92:93], v[218:219]
	v_pk_fma_f32 v[14:15], v[14:15], v[90:91], v[216:217]
	s_waitcnt vmcnt(10)
	v_pk_fma_f32 v[12:13], v[12:13], v[92:93], v[222:223]
	v_pk_fma_f32 v[10:11], v[10:11], v[90:91], v[220:221]
	s_waitcnt vmcnt(9)
	v_pk_fma_f32 v[8:9], v[8:9], v[92:93], v[226:227]
	v_pk_fma_f32 v[6:7], v[6:7], v[90:91], v[224:225]
	s_waitcnt vmcnt(8)
	v_pk_fma_f32 v[4:5], v[4:5], v[92:93], v[230:231]
	v_pk_fma_f32 v[2:3], v[2:3], v[90:91], v[228:229]
	global_store_dwordx4 v[190:191], v[30:33], off offset:576
	global_store_dwordx4 v[188:189], v[26:29], off offset:576
	global_store_dwordx4 v[186:187], v[22:25], off offset:576
	global_store_dwordx4 v[184:185], v[18:21], off offset:576
	global_store_dwordx4 v[182:183], v[14:17], off offset:576
	global_store_dwordx4 v[180:181], v[10:13], off offset:576
	global_store_dwordx4 v[178:179], v[6:9], off offset:576
	global_store_dwordx4 v[176:177], v[2:5], off offset:576
	s_cbranch_vccnz .LBB0_1163
	s_andn2_b64 vcc, exec, s[6:7]
	s_cbranch_vccnz .LBB0_1162
	s_barrier
	s_branch .LBB0_1162

.LBB0_2597:
	s_ashr_i32 s1, s36, 31
	s_add_i32 s0, s36, 0xffffff80
	v_readlane_b32 s22, v242, 19
	s_cmpk_lt_i32 s36, 0x80
	v_readlane_b32 s23, v242, 20
	s_cselect_b32 s13, s45, 0x9000
	s_cselect_b32 s15, s89, s23
	s_cselect_b32 s21, s88, s22
	s_cselect_b32 s0, s36, s0
	s_cselect_b32 s1, s1, 0
	s_cmp_gt_i32 s36, 63
	s_cselect_b32 s13, s13, 0
	s_lshl_b32 s13, s13, 2
	s_add_u32 s22, s35, s13
	v_lshl_or_b32 v106, s46, 8, v165
	s_addc_u32 s23, s37, 0
	s_lshl_b64 s[0:1], s[0:1], 21
	v_ashrrev_i32_e32 v107, 31, v106
	s_add_u32 s0, s21, s0
	v_lshlrev_b64 v[170:171], 2, v[106:107]
	s_addc_u32 s1, s15, s1
	v_lshl_add_u64 v[106:107], s[22:23], 0, v[170:171]
	v_lshl_add_u64 v[170:171], s[0:1], 0, v[170:171]
	v_lshl_add_u64 v[184:185], v[170:171], 0, v[142:143]
	v_lshl_add_u64 v[182:183], v[170:171], 0, v[144:145]
	v_lshl_add_u64 v[180:181], v[170:171], 0, v[146:147]
	v_lshl_add_u64 v[178:179], v[170:171], 0, v[148:149]
	v_lshl_add_u64 v[176:177], v[170:171], 0, v[150:151]
	v_lshl_add_u64 v[174:175], v[170:171], 0, v[152:153]
	v_lshl_add_u64 v[172:173], v[170:171], 0, v[154:155]
	v_lshl_add_u64 v[170:171], v[170:171], 0, v[156:157]
	global_load_dwordx4 v[188:191], v[106:107], off
	global_load_dwordx4 v[192:195], v[106:107], off offset:64
	global_load_dwordx4 v[134:137], v[106:107], off offset:512
	s_nop 0
	global_load_dwordx4 v[106:109], v[106:107], off offset:576
	s_mov_b64 s[0:1], -1
	global_load_dwordx4 v[196:199], v[184:185], off
	global_load_dwordx4 v[200:203], v[182:183], off
	global_load_dwordx4 v[204:207], v[180:181], off
	global_load_dwordx4 v[208:211], v[178:179], off
	global_load_dwordx4 v[212:215], v[176:177], off
	global_load_dwordx4 v[216:219], v[174:175], off
	global_load_dwordx4 v[220:223], v[172:173], off
	global_load_dwordx4 v[224:227], v[170:171], off
	s_andn2_b64 vcc, exec, s[2:3]
	s_waitcnt vmcnt(0)
	v_pk_fma_f32 v[132:133], v[132:133], v[190:191], v[198:199]
	v_pk_fma_f32 v[130:131], v[130:131], v[188:189], v[196:197]
	v_pk_fma_f32 v[128:129], v[128:129], v[190:191], v[202:203]
	v_pk_fma_f32 v[126:127], v[126:127], v[188:189], v[200:201]
	v_pk_fma_f32 v[124:125], v[124:125], v[190:191], v[206:207]
	v_pk_fma_f32 v[122:123], v[122:123], v[188:189], v[204:205]
	v_pk_fma_f32 v[120:121], v[120:121], v[190:191], v[210:211]
	v_pk_fma_f32 v[118:119], v[118:119], v[188:189], v[208:209]
	v_pk_fma_f32 v[116:117], v[116:117], v[190:191], v[214:215]
	v_pk_fma_f32 v[114:115], v[114:115], v[188:189], v[212:213]
	v_pk_fma_f32 v[112:113], v[112:113], v[190:191], v[218:219]
	v_pk_fma_f32 v[110:111], v[110:111], v[188:189], v[216:217]
	v_pk_fma_f32 v[104:105], v[104:105], v[190:191], v[222:223]
	v_pk_fma_f32 v[102:103], v[102:103], v[188:189], v[220:221]
	v_pk_fma_f32 v[100:101], v[100:101], v[190:191], v[226:227]
	v_pk_fma_f32 v[98:99], v[98:99], v[188:189], v[224:225]
	global_load_dwordx4 v[196:199], v[184:185], off offset:64
	global_load_dwordx4 v[200:203], v[182:183], off offset:64
	global_load_dwordx4 v[204:207], v[180:181], off offset:64
	global_load_dwordx4 v[208:211], v[178:179], off offset:64
	global_load_dwordx4 v[212:215], v[176:177], off offset:64
	global_load_dwordx4 v[216:219], v[174:175], off offset:64
	global_load_dwordx4 v[220:223], v[172:173], off offset:64
	global_load_dwordx4 v[224:227], v[170:171], off offset:64
	global_store_dwordx4 v[184:185], v[130:133], off
	global_store_dwordx4 v[182:183], v[126:129], off
	global_store_dwordx4 v[180:181], v[122:125], off
	global_store_dwordx4 v[178:179], v[118:121], off
	global_store_dwordx4 v[176:177], v[114:117], off
	global_store_dwordx4 v[174:175], v[110:113], off
	global_store_dwordx4 v[172:173], v[102:105], off
	global_store_dwordx4 v[170:171], v[98:101], off
	s_waitcnt vmcnt(15)
	v_pk_fma_f32 v[96:97], v[96:97], v[194:195], v[198:199]
	v_pk_fma_f32 v[94:95], v[94:95], v[192:193], v[196:197]
	s_waitcnt vmcnt(14)
	v_pk_fma_f32 v[92:93], v[92:93], v[194:195], v[202:203]
	v_pk_fma_f32 v[90:91], v[90:91], v[192:193], v[200:201]
	s_waitcnt vmcnt(13)
	v_pk_fma_f32 v[88:89], v[88:89], v[194:195], v[206:207]
	v_pk_fma_f32 v[86:87], v[86:87], v[192:193], v[204:205]
	s_waitcnt vmcnt(12)
	v_pk_fma_f32 v[84:85], v[84:85], v[194:195], v[210:211]
	v_pk_fma_f32 v[82:83], v[82:83], v[192:193], v[208:209]
	s_waitcnt vmcnt(11)
	v_pk_fma_f32 v[80:81], v[80:81], v[194:195], v[214:215]
	v_pk_fma_f32 v[78:79], v[78:79], v[192:193], v[212:213]
	s_waitcnt vmcnt(10)
	v_pk_fma_f32 v[76:77], v[76:77], v[194:195], v[218:219]
	v_pk_fma_f32 v[74:75], v[74:75], v[192:193], v[216:217]
	s_waitcnt vmcnt(9)
	v_pk_fma_f32 v[72:73], v[72:73], v[194:195], v[222:223]
	v_pk_fma_f32 v[70:71], v[70:71], v[192:193], v[220:221]
	s_waitcnt vmcnt(8)
	v_pk_fma_f32 v[68:69], v[68:69], v[194:195], v[226:227]
	v_pk_fma_f32 v[66:67], v[66:67], v[192:193], v[224:225]
	global_load_dwordx4 v[196:199], v[184:185], off offset:512
	global_load_dwordx4 v[200:203], v[182:183], off offset:512
	global_load_dwordx4 v[204:207], v[180:181], off offset:512
	global_load_dwordx4 v[208:211], v[178:179], off offset:512
	global_load_dwordx4 v[212:215], v[176:177], off offset:512
	global_load_dwordx4 v[216:219], v[174:175], off offset:512
	global_load_dwordx4 v[220:223], v[172:173], off offset:512
	global_load_dwordx4 v[224:227], v[170:171], off offset:512
	global_store_dwordx4 v[184:185], v[94:97], off offset:64
	global_store_dwordx4 v[182:183], v[90:93], off offset:64
	global_store_dwordx4 v[180:181], v[86:89], off offset:64
	global_store_dwordx4 v[178:179], v[82:85], off offset:64
	global_store_dwordx4 v[176:177], v[78:81], off offset:64
	global_store_dwordx4 v[174:175], v[74:77], off offset:64
	global_store_dwordx4 v[172:173], v[70:73], off offset:64
	global_store_dwordx4 v[170:171], v[66:69], off offset:64
	s_waitcnt vmcnt(15)
	v_pk_fma_f32 v[64:65], v[64:65], v[136:137], v[198:199]
	v_pk_fma_f32 v[62:63], v[62:63], v[134:135], v[196:197]
	s_waitcnt vmcnt(14)
	v_pk_fma_f32 v[60:61], v[60:61], v[136:137], v[202:203]
	v_pk_fma_f32 v[58:59], v[58:59], v[134:135], v[200:201]
	s_waitcnt vmcnt(13)
	v_pk_fma_f32 v[56:57], v[56:57], v[136:137], v[206:207]
	v_pk_fma_f32 v[54:55], v[54:55], v[134:135], v[204:205]
	s_waitcnt vmcnt(12)
	v_pk_fma_f32 v[52:53], v[52:53], v[136:137], v[210:211]
	v_pk_fma_f32 v[50:51], v[50:51], v[134:135], v[208:209]
	s_waitcnt vmcnt(11)
	v_pk_fma_f32 v[48:49], v[48:49], v[136:137], v[214:215]
	v_pk_fma_f32 v[46:47], v[46:47], v[134:135], v[212:213]
	s_waitcnt vmcnt(10)
	v_pk_fma_f32 v[44:45], v[44:45], v[136:137], v[218:219]
	v_pk_fma_f32 v[42:43], v[42:43], v[134:135], v[216:217]
	s_waitcnt vmcnt(9)
	v_pk_fma_f32 v[40:41], v[40:41], v[136:137], v[222:223]
	v_pk_fma_f32 v[38:39], v[38:39], v[134:135], v[220:221]
	s_waitcnt vmcnt(8)
	v_pk_fma_f32 v[36:37], v[36:37], v[136:137], v[226:227]
	v_pk_fma_f32 v[34:35], v[34:35], v[134:135], v[224:225]
	global_load_dwordx4 v[196:199], v[184:185], off offset:576
	global_load_dwordx4 v[200:203], v[182:183], off offset:576
	global_load_dwordx4 v[204:207], v[180:181], off offset:576
	global_load_dwordx4 v[208:211], v[178:179], off offset:576
	global_load_dwordx4 v[212:215], v[176:177], off offset:576
	global_load_dwordx4 v[216:219], v[174:175], off offset:576
	global_load_dwordx4 v[220:223], v[172:173], off offset:576
	global_load_dwordx4 v[224:227], v[170:171], off offset:576
	global_store_dwordx4 v[184:185], v[62:65], off offset:512
	global_store_dwordx4 v[182:183], v[58:61], off offset:512
	global_store_dwordx4 v[180:181], v[54:57], off offset:512
	global_store_dwordx4 v[178:179], v[50:53], off offset:512
	global_store_dwordx4 v[176:177], v[46:49], off offset:512
	global_store_dwordx4 v[174:175], v[42:45], off offset:512
	global_store_dwordx4 v[172:173], v[38:41], off offset:512
	global_store_dwordx4 v[170:171], v[34:37], off offset:512
	s_waitcnt vmcnt(15)
	v_pk_fma_f32 v[32:33], v[32:33], v[108:109], v[198:199]
	v_pk_fma_f32 v[30:31], v[30:31], v[106:107], v[196:197]
	s_waitcnt vmcnt(14)
	v_pk_fma_f32 v[28:29], v[28:29], v[108:109], v[202:203]
	v_pk_fma_f32 v[26:27], v[26:27], v[106:107], v[200:201]
	s_waitcnt vmcnt(13)
	v_pk_fma_f32 v[24:25], v[24:25], v[108:109], v[206:207]
	v_pk_fma_f32 v[22:23], v[22:23], v[106:107], v[204:205]
	s_waitcnt vmcnt(12)
	v_pk_fma_f32 v[20:21], v[20:21], v[108:109], v[210:211]
	v_pk_fma_f32 v[18:19], v[18:19], v[106:107], v[208:209]
	s_waitcnt vmcnt(11)
	v_pk_fma_f32 v[16:17], v[16:17], v[108:109], v[214:215]
	v_pk_fma_f32 v[14:15], v[14:15], v[106:107], v[212:213]
	s_waitcnt vmcnt(10)
	v_pk_fma_f32 v[12:13], v[12:13], v[108:109], v[218:219]
	v_pk_fma_f32 v[10:11], v[10:11], v[106:107], v[216:217]
	s_waitcnt vmcnt(9)
	v_pk_fma_f32 v[8:9], v[8:9], v[108:109], v[222:223]
	v_pk_fma_f32 v[6:7], v[6:7], v[106:107], v[220:221]
	s_waitcnt vmcnt(8)
	v_pk_fma_f32 v[4:5], v[4:5], v[108:109], v[226:227]
	v_pk_fma_f32 v[2:3], v[2:3], v[106:107], v[224:225]
	global_store_dwordx4 v[184:185], v[30:33], off offset:576
	global_store_dwordx4 v[182:183], v[26:29], off offset:576
	global_store_dwordx4 v[180:181], v[22:25], off offset:576
	global_store_dwordx4 v[178:179], v[18:21], off offset:576
	global_store_dwordx4 v[176:177], v[14:17], off offset:576
	global_store_dwordx4 v[174:175], v[10:13], off offset:576
	global_store_dwordx4 v[172:173], v[6:9], off offset:576
	global_store_dwordx4 v[170:171], v[2:5], off offset:576
	s_cbranch_vccnz .LBB0_2586
	s_andn2_b64 vcc, exec, s[6:7]
	s_cbranch_vccnz .LBB0_2585
	s_barrier
	s_branch .LBB0_2585
